# fast body without A-operand selects: own/partner P fragments used directly, V key blocks swapped by per-wave read bases; P fragments written straight to canonical registers
# speedup vs baseline: 1.0138x; 1.0072x over previous
; #define SBAR() __builtin_amdgcn_sched_barrier(0)
; #define KDMA(k0, b) do { const char* g_ = (const char*)(Kh + (long)(k0) * DM); char* l_ = K_lds + (b) * 16384 + wu * 1024; \
;     DMA16(g_ + koff[0], l_); DMA16(g_ + koff[1], l_ + 8192); } while (0)
; #define VDMA(k0, b) do { const char* g_ = (const char*)(Vh + (long)(k0) * DM); char* l_ = V_lds + (b) * 32768 + wu * 1024; \
;     DMA16(g_ + voff[0], l_); DMA16(g_ + voff[1], l_ + 8192); DMA16(g_ + voff[0] + 256, l_ + 16384); DMA16(g_ + voff[1] + 256, l_ + 16384 + 8192); } while (0)
; #define VRD(D0, X) do { X##0 = tr_read<v_rd_off(D0, 0, 0)>(vb); X##1 = tr_read<v_rd_off(D0, 0, 1)>(vb); X##2 = tr_read<v_rd_off(D0, 1, 0)>(vb); X##3 = tr_read<v_rd_off(D0, 1, 1)>(vb); \
;     X##4 = tr_read<v_rd_off(D0, 2, 0)>(vb); X##5 = tr_read<v_rd_off(D0, 2, 1)>(vb); X##6 = tr_read<v_rd_off(D0, 3, 0)>(vb); X##7 = tr_read<v_rd_off(D0, 3, 1)>(vb); } while (0)
; template <int PROBE, int MODE>
; DI void dattn_body(const u16* __restrict__ Qb, const u16* __restrict__ Kh, const u16* __restrict__ Vh, u16* __restrict__ Ob, const u16* __restrict__ O1, float lam, const float* __restrict__ subg, int seq, int q0, float kmax2, char* lds) {
;     ...
;   for (int j = 0; j < NT; ++j) {
;     const bool more = j + 1 < NT;
;     if (!(PROBE & 1)) {
;       if (j + 2 < NT) KDMA((j + 2) * KVBLK, j & 1);
;       if (more) VDMA((j + 1) * KVBLK, (j + 1) & 1);
;     }
;     bf16x8 kf[8];
;     if (more) { const char* Ks_ = K_lds + ((j + 1) & 1) * 16384;
; #pragma unroll
;       for (int d0 = 0; d0 < 8; ++d0) kf[d0] = *reinterpret_cast<const bf16x8*>(Ks_ + KSWZ(32 * kh + r32, (d0 * 16 + hi * 8) * 2)); }
;     const bf16x8 pb0 = *(const bf16x8*)(pr + (j & 1) * 16384), pb1 = *(const bf16x8*)(pr + (j & 1) * 16384 + 16);
;     const int vb = vb0 + (j & 1) * 32768;
;     s16x4 va0, va1, va2, va3, va4, va5, va6, va7, vc0, vc1, vc2, vc3, vc4, vc5, vc6, vc7;
;     VRD(0, va);
;     if (more) { asm volatile("s_waitcnt lgkmcnt(10)" ::: "memory"); SBAR();
;       if (!(PROBE & 4)) { S = f32x16{};
; #pragma unroll
;       for (int d0 = 0; d0 < 8; ++d0) S = __builtin_amdgcn_mfma_f32_32x32x16_bf16(kf[d0], qr[d0], S, 0, 0, 0); }
;       SBAR(); }
;     const bf16x8 A0 = kh ? pb0 : po0, A1 = kh ? pb1 : po1, A2 = kh ? po0 : pb0, A3 = kh ? po1 : pb1;
;     SMX_SETUP(j + 1)
.Lfast0:
	s_sub_i32 s72, s18, 64
	s_and_b32 s101, s25, 0x4000
	s_addk_i32 s25, 0x4000
	s_and_b32 s19, s25, 0x4000
	s_and_b32 s48, s55, 1
	v_lshl_add_u32 v68, s48, 14, v210
	ds_read_b128 v[162:165], v68
	ds_read_b128 v[166:169], v68 offset:16
	v_add_u32_e32 v68, s19, v213
	v_add_u32_e32 v64, v68, v198
	v_add_u32_e32 v69, v68, v199
	ds_read_b128 v[64:67], v64
	ds_read_b128 v[118:121], v69
	v_add_u32_e32 v69, v68, v200
	v_add_u32_e32 v70, v68, v201
	ds_read_b128 v[122:125], v69
	ds_read_b128 v[126:129], v70
	v_add_u32_e32 v69, v68, v202
	v_add_u32_e32 v70, v68, v203
	ds_read_b128 v[134:137], v69
	ds_read_b128 v[138:141], v70
	v_add_u32_e32 v69, v68, v204
	v_add_u32_e32 v68, v68, v205
	ds_read_b128 v[142:145], v69
	ds_read_b128 v[146:149], v68
	s_bfe_u32 s100, s85, 0x1000a
	s_lshl_b32 s100, s100, 13
	s_lshl_b32 s48, s48, 15
	s_sub_i32 s74, s48, s100
	s_add_i32 s48, s48, s100
	v_add_u32_e32 v216, s48, v212
	v_add_u32_e32 v233, s74, v212
	s_cmp_gt_i32 s72, s87
	s_cselect_b32 s100, s21, s20
	v_sub_f32_e32 v160, s100, v158
	s_lshl_b32 s48, s72, 12
	s_add_u32 s48, s16, s48
	s_addc_u32 s49, s17, 0
	s_add_u32 s74, s48, 0x100
	s_addc_u32 s75, s49, 0
	s_and_b32 s100, s54, 0x8000
	s_add_i32 s100, s85, s100
	s_waitcnt lgkmcnt(7)
	v_mfma_f32_32x32x16_bf16 v[64:79], v[64:67], v[82:85], 0
	ds_read_b64_tr_b16 v[234:235], v216 offset:0
	ds_read_b64_tr_b16 v[236:237], v216 offset:0x800
	s_waitcnt lgkmcnt(8)
	v_mfma_f32_32x32x16_bf16 v[64:79], v[118:121], v[86:89], v[64:79]
	ds_read_b64_tr_b16 v[238:239], v216 offset:0x1000
	ds_read_b64_tr_b16 v[240:241], v216 offset:0x1800
	s_waitcnt lgkmcnt(9)
	v_mfma_f32_32x32x16_bf16 v[64:79], v[122:125], v[90:93], v[64:79]
	ds_read_b64_tr_b16 v[242:243], v233 offset:0x2000
	ds_read_b64_tr_b16 v[244:245], v233 offset:0x2800
	s_waitcnt lgkmcnt(10)
	v_mfma_f32_32x32x16_bf16 v[64:79], v[126:129], v[94:97], v[64:79]
	ds_read_b64_tr_b16 v[246:247], v233 offset:0x3000
	ds_read_b64_tr_b16 v[248:249], v233 offset:0x3800
	s_mov_b32 m0, s100
	s_waitcnt lgkmcnt(11)
	v_mfma_f32_32x32x16_bf16 v[64:79], v[134:137], v[98:101], v[64:79]
	global_load_lds_dwordx4 v176, s[48:49]
	s_add_i32 m0, s100, 0x2000
	s_waitcnt lgkmcnt(10)
	v_mfma_f32_32x32x16_bf16 v[64:79], v[138:141], v[102:105], v[64:79]
	global_load_lds_dwordx4 v156, s[48:49]
	s_add_i32 m0, s100, 0x4000
	s_waitcnt lgkmcnt(9)
	v_mfma_f32_32x32x16_bf16 v[64:79], v[142:145], v[106:109], v[64:79]
	global_load_lds_dwordx4 v176, s[74:75]
	s_add_i32 m0, s100, 0x6000
	s_waitcnt lgkmcnt(8)
	v_mfma_f32_32x32x16_bf16 v[64:79], v[146:149], v[110:113], v[64:79]
	global_load_lds_dwordx4 v156, s[74:75]
	s_add_i32 s48, s55, 2
	s_cmp_ge_u32 s48, s11
	s_cbranch_scc1 .Lfast0_k_done
	s_lshl_b32 s48, s18, 12
	s_add_u32 s48, s14, s48
	s_addc_u32 s49, s15, 0
	s_add_i32 s100, s82, s101
	s_mov_b32 m0, s100
	s_nop 0
	global_load_lds_dwordx4 v152, s[48:49]
	s_add_i32 m0, s100, 0x2000
	s_nop 0
	global_load_lds_dwordx4 v154, s[48:49]
; #define DMAWAIT() asm volatile("s_waitcnt vmcnt(0)" ::: "memory")
; #define SMX_FIN(pbuf) do { _Pragma("unroll") for (int r = 0; r < 16; ++r) l_reg += S[r]; \
;     PK4S(0, po0); PK4S(8, po1); \
;     *(bf16x8*)(pw + (pbuf) * 16384) = po0; *(bf16x8*)(pw + (pbuf) * 16384 + 16) = po1; } while (0)
; #define VRD(D0, X) do { X##0 = tr_read<v_rd_off(D0, 0, 0)>(vb); X##1 = tr_read<v_rd_off(D0, 0, 1)>(vb); X##2 = tr_read<v_rd_off(D0, 1, 0)>(vb); X##3 = tr_read<v_rd_off(D0, 1, 1)>(vb); \
;     X##4 = tr_read<v_rd_off(D0, 2, 0)>(vb); X##5 = tr_read<v_rd_off(D0, 2, 1)>(vb); X##6 = tr_read<v_rd_off(D0, 3, 0)>(vb); X##7 = tr_read<v_rd_off(D0, 3, 1)>(vb); } while (0)
; #define LWAIT() do { asm volatile("s_waitcnt lgkmcnt(0)" ::: "memory"); SBAR(); } while (0)
; #define VMMP(D0, X) do { if (!(PROBE & 8)) VMM(D0, X); } while (0)
; #define SMXP(c) do { if (!(PROBE & 2)) { if (more) SMX_CH(c); } } while (0)
; template <int PROBE, int MODE>
; DI void dattn_body(const u16* __restrict__ Qb, const u16* __restrict__ Kh, const u16* __restrict__ Vh, u16* __restrict__ Ob, const u16* __restrict__ O1, float lam, const float* __restrict__ subg, int seq, int q0, float kmax2, char* lds) {
;     ...
;     LWAIT(); VRD(1, vc); VMMP(0, va); SMXP(0);
;     LWAIT(); VRD(2, va); VMMP(1, vc); SMXP(1);
;     LWAIT(); VRD(3, vc); VMMP(2, va); SMXP(2);
;     LWAIT(); VMMP(3, vc); SMXP(3);
;     if (!(PROBE & 2)) { if (more) SMX_FIN((j + 1) & 1); }
;     DMAWAIT();
;     __syncthreads();
.Lfast0_k_done:
	s_waitcnt lgkmcnt(6)
	v_mfma_f32_32x32x16_bf16 v[0:15], v[114:117], v[234:237], v[0:15]
	ds_read_b64_tr_b16 v[138:139], v216 offset:0x200
	ds_read_b64_tr_b16 v[140:141], v216 offset:0xa00
	s_waitcnt lgkmcnt(6)
	v_mfma_f32_32x32x16_bf16 v[0:15], v[130:133], v[238:241], v[0:15]
	ds_read_b64_tr_b16 v[142:143], v216 offset:0x1200
	ds_read_b64_tr_b16 v[144:145], v216 offset:0x1a00
	s_nop 1
	v_fma_f32 v118, v64, s12, v160
	v_fma_f32 v119, v65, s12, v160
	v_fma_f32 v120, v66, s12, v160
	v_fma_f32 v121, v67, s12, v160
	s_waitcnt lgkmcnt(6)
	v_mfma_f32_32x32x16_bf16 v[0:15], v[162:165], v[242:245], v[0:15]
	ds_read_b64_tr_b16 v[134:135], v233 offset:0x2200
	ds_read_b64_tr_b16 v[136:137], v233 offset:0x2a00
	v_fma_f32 v122, v68, s12, v160
	v_fma_f32 v123, v69, s12, v160
	v_exp_f32_e32 v118, v118
	v_exp_f32_e32 v119, v119
	s_waitcnt lgkmcnt(6)
	v_mfma_f32_32x32x16_bf16 v[0:15], v[166:169], v[246:249], v[0:15]
	ds_read_b64_tr_b16 v[126:127], v233 offset:0x3200
	ds_read_b64_tr_b16 v[128:129], v233 offset:0x3a00
	v_fma_f32 v124, v70, s12, v160
	v_fma_f32 v125, v71, s12, v160
	v_exp_f32_e32 v120, v120
	v_exp_f32_e32 v121, v121
	s_waitcnt lgkmcnt(6)
	v_mfma_f32_32x32x16_bf16 v[16:31], v[114:117], v[138:141], v[16:31]
	ds_read_b64_tr_b16 v[146:147], v216 offset:0x400
	ds_read_b64_tr_b16 v[148:149], v216 offset:0xc00
	v_exp_f32_e32 v122, v122
	v_exp_f32_e32 v123, v123
	v_add_f32_e32 v209, v118, v209
	v_add_f32_e32 v209, v119, v209
	s_waitcnt lgkmcnt(6)
	v_mfma_f32_32x32x16_bf16 v[16:31], v[130:133], v[142:145], v[16:31]
	ds_read_b64_tr_b16 v[142:143], v216 offset:0x1400
	ds_read_b64_tr_b16 v[144:145], v216 offset:0x1c00
	v_exp_f32_e32 v124, v124
	v_exp_f32_e32 v125, v125
	v_add_f32_e32 v209, v120, v209
	v_add_f32_e32 v209, v121, v209
	v_fma_f32 v244, v72, s12, v160
	v_fma_f32 v245, v73, s12, v160
	s_waitcnt lgkmcnt(6)
	v_mfma_f32_32x32x16_bf16 v[16:31], v[162:165], v[134:137], v[16:31]
	ds_read_b64_tr_b16 v[138:139], v233 offset:0x2400
	ds_read_b64_tr_b16 v[140:141], v233 offset:0x2c00
	v_fma_f32 v246, v74, s12, v160
	v_fma_f32 v247, v75, s12, v160
	v_add_f32_e32 v209, v122, v209
	v_add_f32_e32 v209, v123, v209
	s_waitcnt lgkmcnt(6)
	v_mfma_f32_32x32x16_bf16 v[16:31], v[166:169], v[126:129], v[16:31]
	ds_read_b64_tr_b16 v[64:65], v233 offset:0x3400
	ds_read_b64_tr_b16 v[66:67], v233 offset:0x3c00
	v_fma_f32 v76, v76, s12, v160
	v_fma_f32 v77, v77, s12, v160
	v_fma_f32 v78, v78, s12, v160
	v_fma_f32 v79, v79, s12, v160
	s_waitcnt lgkmcnt(6)
	v_mfma_f32_32x32x16_bf16 v[32:47], v[114:117], v[146:149], v[32:47]
	v_exp_f32_e32 v244, v244
	v_exp_f32_e32 v245, v245
	v_add_f32_e32 v209, v124, v209
	v_add_f32_e32 v209, v125, v209
	s_waitcnt lgkmcnt(4)
	v_mfma_f32_32x32x16_bf16 v[32:47], v[130:133], v[142:145], v[32:47]
	ds_read_b64_tr_b16 v[142:143], v216 offset:0x600
	ds_read_b64_tr_b16 v[144:145], v216 offset:0xe00
	ds_read_b64_tr_b16 v[126:127], v216 offset:0x1600
	ds_read_b64_tr_b16 v[128:129], v216 offset:0x1e00
	v_exp_f32_e32 v246, v246
	v_exp_f32_e32 v247, v247
	s_waitcnt lgkmcnt(6)
	v_mfma_f32_32x32x16_bf16 v[32:47], v[162:165], v[138:141], v[32:47]
	ds_read_b64_tr_b16 v[134:135], v233 offset:0x2600
	ds_read_b64_tr_b16 v[136:137], v233 offset:0x2e00
	v_exp_f32_e32 v76, v76
	v_exp_f32_e32 v77, v77
	v_add_f32_e32 v209, v244, v209
	v_add_f32_e32 v209, v245, v209
	s_waitcnt lgkmcnt(6)
	v_mfma_f32_32x32x16_bf16 v[32:47], v[166:169], v[64:67], v[32:47]
	ds_read_b64_tr_b16 v[68:69], v233 offset:0x3600
	ds_read_b64_tr_b16 v[70:71], v233 offset:0x3e00
	v_exp_f32_e32 v78, v78
	v_exp_f32_e32 v79, v79
	v_add_f32_e32 v209, v246, v209
	v_add_f32_e32 v209, v247, v209
	s_waitcnt lgkmcnt(6)
	v_mfma_f32_32x32x16_bf16 v[48:63], v[114:117], v[142:145], v[48:63]
	v_add_u32_e32 v64, s19, v211
	v_add_f32_e32 v209, v76, v209
	v_add_f32_e32 v209, v77, v209
	v_cvt_pk_bf16_f32 v114, v118, v119
	v_cvt_pk_bf16_f32 v115, v120, v121
	v_cvt_pk_bf16_f32 v116, v122, v123
	v_cvt_pk_bf16_f32 v117, v124, v125
	s_waitcnt lgkmcnt(4)
	v_mfma_f32_32x32x16_bf16 v[48:63], v[130:133], v[126:129], v[48:63]
	v_add_f32_e32 v209, v78, v209
	v_add_f32_e32 v209, v79, v209
	v_permlane32_swap_b32_e32 v114, v116
	v_permlane32_swap_b32_e32 v115, v117
	v_cvt_pk_bf16_f32 v130, v244, v245
	v_cvt_pk_bf16_f32 v131, v246, v247
	v_cvt_pk_bf16_f32 v132, v76, v77
	v_cvt_pk_bf16_f32 v133, v78, v79
	s_waitcnt lgkmcnt(2)
	v_mfma_f32_32x32x16_bf16 v[48:63], v[162:165], v[134:137], v[48:63]
	ds_write_b128 v64, v[114:117]
	v_permlane32_swap_b32_e32 v130, v132
	v_permlane32_swap_b32_e32 v131, v133
	s_waitcnt lgkmcnt(1)
	v_mfma_f32_32x32x16_bf16 v[48:63], v[166:169], v[68:71], v[48:63]
	ds_write_b128 v64, v[130:133] offset:16
	s_add_i32 s55, s55, 1
	s_add_i32 s18, s18, 64
	s_add_i32 s54, s54, 0x8000
	s_cmp_eq_u32 s83, s55
	s_waitcnt vmcnt(0) lgkmcnt(0)
	s_barrier
	s_cbranch_scc1 .LBB0_265
	s_branch .LBB0_247

; #define SBAR() __builtin_amdgcn_sched_barrier(0)
; #define KDMA(k0, b) do { const char* g_ = (const char*)(Kh + (long)(k0) * DM); char* l_ = K_lds + (b) * 16384 + wu * 1024; \
;     DMA16(g_ + koff[0], l_); DMA16(g_ + koff[1], l_ + 8192); } while (0)
; #define VDMA(k0, b) do { const char* g_ = (const char*)(Vh + (long)(k0) * DM); char* l_ = V_lds + (b) * 32768 + wu * 1024; \
;     DMA16(g_ + voff[0], l_); DMA16(g_ + voff[1], l_ + 8192); DMA16(g_ + voff[0] + 256, l_ + 16384); DMA16(g_ + voff[1] + 256, l_ + 16384 + 8192); } while (0)
; #define VRD(D0, X) do { X##0 = tr_read<v_rd_off(D0, 0, 0)>(vb); X##1 = tr_read<v_rd_off(D0, 0, 1)>(vb); X##2 = tr_read<v_rd_off(D0, 1, 0)>(vb); X##3 = tr_read<v_rd_off(D0, 1, 1)>(vb); \
;     X##4 = tr_read<v_rd_off(D0, 2, 0)>(vb); X##5 = tr_read<v_rd_off(D0, 2, 1)>(vb); X##6 = tr_read<v_rd_off(D0, 3, 0)>(vb); X##7 = tr_read<v_rd_off(D0, 3, 1)>(vb); } while (0)
; template <int PROBE, int MODE>
; DI void dattn_body(const u16* __restrict__ Qb, const u16* __restrict__ Kh, const u16* __restrict__ Vh, u16* __restrict__ Ob, const u16* __restrict__ O1, float lam, const float* __restrict__ subg, int seq, int q0, float kmax2, char* lds) {
;     ...
;   for (int j = 0; j < NT; ++j) {
;     const bool more = j + 1 < NT;
;     if (!(PROBE & 1)) {
;       if (j + 2 < NT) KDMA((j + 2) * KVBLK, j & 1);
;       if (more) VDMA((j + 1) * KVBLK, (j + 1) & 1);
;     }
;     bf16x8 kf[8];
;     if (more) { const char* Ks_ = K_lds + ((j + 1) & 1) * 16384;
; #pragma unroll
;       for (int d0 = 0; d0 < 8; ++d0) kf[d0] = *reinterpret_cast<const bf16x8*>(Ks_ + KSWZ(32 * kh + r32, (d0 * 16 + hi * 8) * 2)); }
;     const bf16x8 pb0 = *(const bf16x8*)(pr + (j & 1) * 16384), pb1 = *(const bf16x8*)(pr + (j & 1) * 16384 + 16);
;     const int vb = vb0 + (j & 1) * 32768;
;     s16x4 va0, va1, va2, va3, va4, va5, va6, va7, vc0, vc1, vc2, vc3, vc4, vc5, vc6, vc7;
;     VRD(0, va);
;     if (more) { asm volatile("s_waitcnt lgkmcnt(10)" ::: "memory"); SBAR();
;       if (!(PROBE & 4)) { S = f32x16{};
; #pragma unroll
;       for (int d0 = 0; d0 < 8; ++d0) S = __builtin_amdgcn_mfma_f32_32x32x16_bf16(kf[d0], qr[d0], S, 0, 0, 0); }
;       SBAR(); }
;     const bf16x8 A0 = kh ? pb0 : po0, A1 = kh ? pb1 : po1, A2 = kh ? po0 : pb0, A3 = kh ? po1 : pb1;
;     SMX_SETUP(j + 1)
.Lfast1:
	s_sub_i32 s72, s0, 64
	s_and_b32 s101, s24, 0x4000
	s_addk_i32 s24, 0x4000
	s_and_b32 s1, s24, 0x4000
	s_and_b32 s4, s40, 1
	v_lshl_add_u32 v68, s4, 14, v209
	ds_read_b128 v[162:165], v68
	ds_read_b128 v[166:169], v68 offset:16
	v_add_u32_e32 v68, s1, v212
	v_add_u32_e32 v64, v68, v196
	v_add_u32_e32 v69, v68, v198
	ds_read_b128 v[64:67], v64
	ds_read_b128 v[118:121], v69
	v_add_u32_e32 v69, v68, v199
	v_add_u32_e32 v70, v68, v200
	ds_read_b128 v[122:125], v69
	ds_read_b128 v[126:129], v70
	v_add_u32_e32 v69, v68, v201
	v_add_u32_e32 v70, v68, v202
	ds_read_b128 v[134:137], v69
	ds_read_b128 v[138:141], v70
	v_add_u32_e32 v69, v68, v203
	v_add_u32_e32 v68, v68, v204
	ds_read_b128 v[142:145], v69
	ds_read_b128 v[146:149], v68
	s_bfe_u32 s100, s39, 0x1000a
	s_lshl_b32 s100, s100, 13
	s_lshl_b32 s4, s4, 15
	s_sub_i32 s18, s4, s100
	s_add_i32 s4, s4, s100
	v_add_u32_e32 v215, s4, v211
	v_add_u32_e32 v233, s18, v211
	s_cmp_gt_i32 s72, s87
	s_cselect_b32 s100, s21, s20
	v_sub_f32_e32 v160, s100, v158
	s_lshl_b32 s4, s72, 12
	s_add_u32 s4, s16, s4
	s_addc_u32 s5, s17, 0
	s_add_u32 s18, s4, 0x100
	s_addc_u32 s19, s5, 0
	s_and_b32 s100, s25, 0x8000
	s_add_i32 s100, s39, s100
	s_waitcnt lgkmcnt(7)
	v_mfma_f32_32x32x16_bf16 v[64:79], v[64:67], v[82:85], 0
	ds_read_b64_tr_b16 v[234:235], v215 offset:0
	ds_read_b64_tr_b16 v[236:237], v215 offset:0x800
	s_waitcnt lgkmcnt(8)
	v_mfma_f32_32x32x16_bf16 v[64:79], v[118:121], v[86:89], v[64:79]
	ds_read_b64_tr_b16 v[238:239], v215 offset:0x1000
	ds_read_b64_tr_b16 v[240:241], v215 offset:0x1800
	s_waitcnt lgkmcnt(9)
	v_mfma_f32_32x32x16_bf16 v[64:79], v[122:125], v[90:93], v[64:79]
	ds_read_b64_tr_b16 v[242:243], v233 offset:0x2000
	ds_read_b64_tr_b16 v[244:245], v233 offset:0x2800
	s_waitcnt lgkmcnt(10)
	v_mfma_f32_32x32x16_bf16 v[64:79], v[126:129], v[94:97], v[64:79]
	ds_read_b64_tr_b16 v[246:247], v233 offset:0x3000
	ds_read_b64_tr_b16 v[248:249], v233 offset:0x3800
	s_mov_b32 m0, s100
	s_waitcnt lgkmcnt(11)
	v_mfma_f32_32x32x16_bf16 v[64:79], v[134:137], v[98:101], v[64:79]
	global_load_lds_dwordx4 v152, s[4:5]
	s_add_i32 m0, s100, 0x2000
	s_waitcnt lgkmcnt(10)
	v_mfma_f32_32x32x16_bf16 v[64:79], v[138:141], v[102:105], v[64:79]
	global_load_lds_dwordx4 v156, s[4:5]
	s_add_i32 m0, s100, 0x4000
	s_waitcnt lgkmcnt(9)
	v_mfma_f32_32x32x16_bf16 v[64:79], v[142:145], v[106:109], v[64:79]
	global_load_lds_dwordx4 v152, s[18:19]
	s_add_i32 m0, s100, 0x6000
	s_waitcnt lgkmcnt(8)
	v_mfma_f32_32x32x16_bf16 v[64:79], v[146:149], v[110:113], v[64:79]
	global_load_lds_dwordx4 v156, s[18:19]
	s_add_i32 s4, s40, 2
	s_cmp_ge_u32 s4, s11
	s_cbranch_scc1 .Lfast1_k_done
	s_lshl_b32 s4, s0, 12
	s_add_u32 s4, s14, s4
	s_addc_u32 s5, s15, 0
	s_add_u32 s4, s4, 0x100
	s_addc_u32 s5, s5, 0
	s_add_i32 s100, s38, s101
	s_mov_b32 m0, s100
	s_nop 0
	global_load_lds_dwordx4 v176, s[4:5]
	s_add_i32 m0, s100, 0x2000
	s_nop 0
	global_load_lds_dwordx4 v154, s[4:5]
; #define DMAWAIT() asm volatile("s_waitcnt vmcnt(0)" ::: "memory")
; #define SMX_FIN(pbuf) do { _Pragma("unroll") for (int r = 0; r < 16; ++r) l_reg += S[r]; \
;     PK4S(0, po0); PK4S(8, po1); \
;     *(bf16x8*)(pw + (pbuf) * 16384) = po0; *(bf16x8*)(pw + (pbuf) * 16384 + 16) = po1; } while (0)
; #define VRD(D0, X) do { X##0 = tr_read<v_rd_off(D0, 0, 0)>(vb); X##1 = tr_read<v_rd_off(D0, 0, 1)>(vb); X##2 = tr_read<v_rd_off(D0, 1, 0)>(vb); X##3 = tr_read<v_rd_off(D0, 1, 1)>(vb); \
;     X##4 = tr_read<v_rd_off(D0, 2, 0)>(vb); X##5 = tr_read<v_rd_off(D0, 2, 1)>(vb); X##6 = tr_read<v_rd_off(D0, 3, 0)>(vb); X##7 = tr_read<v_rd_off(D0, 3, 1)>(vb); } while (0)
; #define LWAIT() do { asm volatile("s_waitcnt lgkmcnt(0)" ::: "memory"); SBAR(); } while (0)
; #define VMMP(D0, X) do { if (!(PROBE & 8)) VMM(D0, X); } while (0)
; #define SMXP(c) do { if (!(PROBE & 2)) { if (more) SMX_CH(c); } } while (0)
; template <int PROBE, int MODE>
; DI void dattn_body(const u16* __restrict__ Qb, const u16* __restrict__ Kh, const u16* __restrict__ Vh, u16* __restrict__ Ob, const u16* __restrict__ O1, float lam, const float* __restrict__ subg, int seq, int q0, float kmax2, char* lds) {
;     ...
;     LWAIT(); VRD(1, vc); VMMP(0, va); SMXP(0);
;     LWAIT(); VRD(2, va); VMMP(1, vc); SMXP(1);
;     LWAIT(); VRD(3, vc); VMMP(2, va); SMXP(2);
;     LWAIT(); VMMP(3, vc); SMXP(3);
;     if (!(PROBE & 2)) { if (more) SMX_FIN((j + 1) & 1); }
;     DMAWAIT();
;     __syncthreads();
.Lfast1_k_done:
	s_waitcnt lgkmcnt(6)
	v_mfma_f32_32x32x16_bf16 v[0:15], v[114:117], v[234:237], v[0:15]
	ds_read_b64_tr_b16 v[138:139], v215 offset:0x200
	ds_read_b64_tr_b16 v[140:141], v215 offset:0xa00
	s_waitcnt lgkmcnt(6)
	v_mfma_f32_32x32x16_bf16 v[0:15], v[130:133], v[238:241], v[0:15]
	ds_read_b64_tr_b16 v[142:143], v215 offset:0x1200
	ds_read_b64_tr_b16 v[144:145], v215 offset:0x1a00
	s_nop 1
	v_fma_f32 v118, v64, s12, v160
	v_fma_f32 v119, v65, s12, v160
	v_fma_f32 v120, v66, s12, v160
	v_fma_f32 v121, v67, s12, v160
	s_waitcnt lgkmcnt(6)
	v_mfma_f32_32x32x16_bf16 v[0:15], v[162:165], v[242:245], v[0:15]
	ds_read_b64_tr_b16 v[134:135], v233 offset:0x2200
	ds_read_b64_tr_b16 v[136:137], v233 offset:0x2a00
	v_fma_f32 v122, v68, s12, v160
	v_fma_f32 v123, v69, s12, v160
	v_exp_f32_e32 v118, v118
	v_exp_f32_e32 v119, v119
	s_waitcnt lgkmcnt(6)
	v_mfma_f32_32x32x16_bf16 v[0:15], v[166:169], v[246:249], v[0:15]
	ds_read_b64_tr_b16 v[126:127], v233 offset:0x3200
	ds_read_b64_tr_b16 v[128:129], v233 offset:0x3a00
	v_fma_f32 v124, v70, s12, v160
	v_fma_f32 v125, v71, s12, v160
	v_exp_f32_e32 v120, v120
	v_exp_f32_e32 v121, v121
	s_waitcnt lgkmcnt(6)
	v_mfma_f32_32x32x16_bf16 v[16:31], v[114:117], v[138:141], v[16:31]
	ds_read_b64_tr_b16 v[146:147], v215 offset:0x400
	ds_read_b64_tr_b16 v[148:149], v215 offset:0xc00
	v_exp_f32_e32 v122, v122
	v_exp_f32_e32 v123, v123
	v_add_f32_e32 v208, v118, v208
	v_add_f32_e32 v208, v119, v208
	s_waitcnt lgkmcnt(6)
	v_mfma_f32_32x32x16_bf16 v[16:31], v[130:133], v[142:145], v[16:31]
	ds_read_b64_tr_b16 v[142:143], v215 offset:0x1400
	ds_read_b64_tr_b16 v[144:145], v215 offset:0x1c00
	v_exp_f32_e32 v124, v124
	v_exp_f32_e32 v125, v125
	v_add_f32_e32 v208, v120, v208
	v_add_f32_e32 v208, v121, v208
	v_fma_f32 v244, v72, s12, v160
	v_fma_f32 v245, v73, s12, v160
	s_waitcnt lgkmcnt(6)
	v_mfma_f32_32x32x16_bf16 v[16:31], v[162:165], v[134:137], v[16:31]
	ds_read_b64_tr_b16 v[138:139], v233 offset:0x2400
	ds_read_b64_tr_b16 v[140:141], v233 offset:0x2c00
	v_fma_f32 v246, v74, s12, v160
	v_fma_f32 v247, v75, s12, v160
	v_add_f32_e32 v208, v122, v208
	v_add_f32_e32 v208, v123, v208
	s_waitcnt lgkmcnt(6)
	v_mfma_f32_32x32x16_bf16 v[16:31], v[166:169], v[126:129], v[16:31]
	ds_read_b64_tr_b16 v[64:65], v233 offset:0x3400
	ds_read_b64_tr_b16 v[66:67], v233 offset:0x3c00
	v_fma_f32 v76, v76, s12, v160
	v_fma_f32 v77, v77, s12, v160
	v_fma_f32 v78, v78, s12, v160
	v_fma_f32 v79, v79, s12, v160
	s_waitcnt lgkmcnt(6)
	v_mfma_f32_32x32x16_bf16 v[32:47], v[114:117], v[146:149], v[32:47]
	v_exp_f32_e32 v244, v244
	v_exp_f32_e32 v245, v245
	v_add_f32_e32 v208, v124, v208
	v_add_f32_e32 v208, v125, v208
	s_waitcnt lgkmcnt(4)
	v_mfma_f32_32x32x16_bf16 v[32:47], v[130:133], v[142:145], v[32:47]
	ds_read_b64_tr_b16 v[142:143], v215 offset:0x600
	ds_read_b64_tr_b16 v[144:145], v215 offset:0xe00
	ds_read_b64_tr_b16 v[126:127], v215 offset:0x1600
	ds_read_b64_tr_b16 v[128:129], v215 offset:0x1e00
	v_exp_f32_e32 v246, v246
	v_exp_f32_e32 v247, v247
	s_waitcnt lgkmcnt(6)
	v_mfma_f32_32x32x16_bf16 v[32:47], v[162:165], v[138:141], v[32:47]
	ds_read_b64_tr_b16 v[134:135], v233 offset:0x2600
	ds_read_b64_tr_b16 v[136:137], v233 offset:0x2e00
	v_exp_f32_e32 v76, v76
	v_exp_f32_e32 v77, v77
	v_add_f32_e32 v208, v244, v208
	v_add_f32_e32 v208, v245, v208
	s_waitcnt lgkmcnt(6)
	v_mfma_f32_32x32x16_bf16 v[32:47], v[166:169], v[64:67], v[32:47]
	ds_read_b64_tr_b16 v[68:69], v233 offset:0x3600
	ds_read_b64_tr_b16 v[70:71], v233 offset:0x3e00
	v_exp_f32_e32 v78, v78
	v_exp_f32_e32 v79, v79
	v_add_f32_e32 v208, v246, v208
	v_add_f32_e32 v208, v247, v208
	s_waitcnt lgkmcnt(6)
	v_mfma_f32_32x32x16_bf16 v[48:63], v[114:117], v[142:145], v[48:63]
	v_add_u32_e32 v64, s1, v210
	v_add_f32_e32 v208, v76, v208
	v_add_f32_e32 v208, v77, v208
	v_cvt_pk_bf16_f32 v114, v118, v119
	v_cvt_pk_bf16_f32 v115, v120, v121
	v_cvt_pk_bf16_f32 v116, v122, v123
	v_cvt_pk_bf16_f32 v117, v124, v125
	s_waitcnt lgkmcnt(4)
	v_mfma_f32_32x32x16_bf16 v[48:63], v[130:133], v[126:129], v[48:63]
	v_add_f32_e32 v208, v78, v208
	v_add_f32_e32 v208, v79, v208
	v_permlane32_swap_b32_e32 v114, v116
	v_permlane32_swap_b32_e32 v115, v117
	v_cvt_pk_bf16_f32 v130, v244, v245
	v_cvt_pk_bf16_f32 v131, v246, v247
	v_cvt_pk_bf16_f32 v132, v76, v77
	v_cvt_pk_bf16_f32 v133, v78, v79
	s_waitcnt lgkmcnt(2)
	v_mfma_f32_32x32x16_bf16 v[48:63], v[162:165], v[134:137], v[48:63]
	ds_write_b128 v64, v[114:117]
	v_permlane32_swap_b32_e32 v130, v132
	v_permlane32_swap_b32_e32 v131, v133
	s_waitcnt lgkmcnt(1)
	v_mfma_f32_32x32x16_bf16 v[48:63], v[166:169], v[68:71], v[48:63]
	ds_write_b128 v64, v[130:133] offset:16
	s_add_i32 s40, s40, 1
	s_add_i32 s0, s0, 64
	s_add_i32 s25, s25, 0x8000
	s_cmp_eq_u32 s83, s40
	s_waitcnt vmcnt(0) lgkmcnt(0)
	s_barrier
	s_cbranch_scc1 .LBB0_303
	s_branch .LBB0_285
